# T GEMM third round (4 tiles) handed to idle scan WGs 0-3; attention WGs do two rounds
# speedup vs baseline: 1.0051x; 1.0051x over previous
;     __device__ __forceinline__ unsigned char* ws() const { return (unsigned char*)ptr(37); }
; #define ws (p.ws())
; __device__ __forceinline__ void sub_barrier(const Ctx& p, unsigned n) {
;     asm volatile("s_waitcnt vmcnt(0)" ::: "memory");
;     __syncthreads();
;     if (threadIdx.x == 0) {
;         unsigned* c = (unsigned*)(p.ws() + WS_CTR) + 128;
;         __builtin_amdgcn_fence(__ATOMIC_RELEASE, "agent");
;         asm volatile("s_waitcnt vmcnt(0)" ::: "memory");
;         __hip_atomic_fetch_add(c, 1u, __ATOMIC_RELAXED, __HIP_MEMORY_SCOPE_AGENT);
;         while (__hip_atomic_load(c, __ATOMIC_RELAXED, __HIP_MEMORY_SCOPE_AGENT) < n) __builtin_amdgcn_s_sleep(20);
;         __builtin_amdgcn_fence(__ATOMIC_ACQUIRE, "agent");
;         asm volatile("s_waitcnt vmcnt(0)" ::: "memory");
;     }
;     __syncthreads();
; }
; __global__ void __launch_bounds__(512) fwd_kernel(Params prm) {
;     ...
;         if (blockIdx.x >= 128) {
;             sub_barrier(p, 128u);
;             EpiGate1 E{(bf16_t*)(ws + WS_KB), (const bf16_t*)(ws + WS_GATE)};
;             pg8::Gemm g{(const bf16_t*)(ws + WS_QB), (const bf16_t*)(ws + WS_WAT), MP, DM, 512, 512}; pg8::StaticOrder S; S.init(MP, DM, 128, (int)blockIdx.x - 128);
;             pg8::gemm_phase<EpiGate1, pg8::StaticOrder, true, true>(lds, g, S, E);
.Lffn2w_done:
	s_cmpk_gt_u32 s28, 3
	s_cbranch_scc1 .Ltg_scan_skip
	s_waitcnt vmcnt(0) lgkmcnt(0)
	s_barrier
	v_cmp_eq_u32_e32 vcc, 0, v180
	s_and_saveexec_b64 s[2:3], vcc
	s_cbranch_execz .Ltg_sync_done
	v_mov_b32_e32 v0, 0x23528
	ds_read_b64 v[0:1], v0
	s_waitcnt lgkmcnt(0)
	v_readfirstlane_b32 s4, v0
	v_readfirstlane_b32 s5, v1
	s_nop 4
	s_add_u32 s4, s4, 0x3180200
	s_addc_u32 s5, s5, 0
	v_mov_b32_e32 v0, 0

;     __device__ __forceinline__ unsigned char* ws() const { return (unsigned char*)ptr(37); }
;     __device__ __forceinline__ bool next(int i, pg8::Unit& u) const { if (i > 0 || !on) return false; u.pm = 0; u.pn = pn; return true; }
; #define ws (p.ws())
;     __host__ __device__ bool next(int i, Unit& u) const {
;         const long L = (long)i * G + c; if (L >= nwg) return false;
;         int wgid = (int)L; { const int q = nwg / NXCD, r = nwg % NXCD, xcd = wgid % NXCD, off = wgid / NXCD; wgid = (xcd < r ? xcd * (q + 1) : r * (q + 1) + (xcd - r) * q) + off; }
;         const int nig = WGM * nN, gid = wgid / nig, fm = gid * WGM, gsz = (nM - fm) < WGM ? (nM - fm) : WGM;
;         u.pm = fm + ((wgid % nig) % gsz); u.pn = (wgid % nig) / gsz; return true;
; __global__ void __launch_bounds__(512) fwd_kernel(Params prm) {
;     ...
;             pg8::Gemm g{(const bf16_t*)(ws + WS_QB), (const bf16_t*)(ws + WS_WAT), MP, DM, 512, 512}; pg8::StaticOrder S; S.init(MP, DM, 128, (int)blockIdx.x - 128);
;             pg8::gemm_phase<EpiGate1, pg8::StaticOrder, true, true>(lds, g, S, E);
.Ltg_sync_done:
	s_or_b64 exec, exec, s[2:3]
	v_mov_b32_e32 v0, 0x23528
	ds_read_b64 v[0:1], v0
	s_waitcnt lgkmcnt(0)
	s_barrier
	v_readfirstlane_b32 s10, v0
	v_readfirstlane_b32 s11, v1
	v_readfirstlane_b32 s14, v180
	s_nop 4
	s_add_i32 s33, s28, 0x100
	s_mov_b64 s[2:3], -1
	s_branch .Ltg_entry

;     __device__ __forceinline__ bool next(int i, pg8::Unit& u) const { if (i > 0 || !on) return false; u.pm = 0; u.pn = pn; return true; }
;     __host__ __device__ bool next(int i, Unit& u) const {
;         const long L = (long)i * G + c; if (L >= nwg) return false;
;         int wgid = (int)L; { const int q = nwg / NXCD, r = nwg % NXCD, xcd = wgid % NXCD, off = wgid / NXCD; wgid = (xcd < r ? xcd * (q + 1) : r * (q + 1) + (xcd - r) * q) + off; }
;         const int nig = WGM * nN, gid = wgid / nig, fm = gid * WGM, gsz = (nM - fm) < WGM ? (nM - fm) : WGM;
;         u.pm = fm + ((wgid % nig) % gsz); u.pn = (wgid % nig) / gsz; return true;
.Ltg_entry:
	s_ashr_i32 s4, s33, 31
	s_lshr_b32 s4, s4, 29
	s_add_i32 s7, s33, s4
	s_and_b32 s4, s7, -8
	s_sub_i32 s6, s33, s4
	s_cmp_gt_i32 s6, 3
	s_cbranch_scc0 .LBB0_1830
	s_lshl_b32 s4, s6, 5
	s_or_b32 s8, s4, 4
	s_ashr_i32 s4, s7, 3
	s_cbranch_execz .LBB0_1831
	s_branch .LBB0_1832

; #define PG8_STAGE(bufoff, gbase, voff) do { _Pragma("unroll") for (int _i = 0; _i < 2; ++_i) \
;         __builtin_amdgcn_global_load_lds((const unsigned*)((const char*)(gbase) + (voff)[_i]), (PG8_LAS unsigned*)(lds + (bufoff) + ldsw + _i * 8192), 16, 0, 0); } while (0)
; #define PG8_WAIT_V(n) asm volatile("s_waitcnt vmcnt(" #n ")" ::: "memory")
; #define PG8_BAR __builtin_amdgcn_s_barrier()
; template <class Epi, class Sched, bool ALIGN_EPI = false, bool SP2 = false>
; __device__ __forceinline__ void gemm_phase(PG8_LAS unsigned char* lds, const Gemm g, const Sched& S, const Epi& E) {
;     const int tid = threadIdx.x, wid = __builtin_amdgcn_readfirstlane(tid >> 6), lane = tid & 63, wr = wid >> 2, wc = wid & 3, fr = lane & 15, fq = lane >> 4;
;     const int K = g.K, nt = K / BK;
;     unsigned voffA[2], voffB[2];
; #pragma unroll
;     for (int i = 0; i < 2; ++i) { int R, C; stage_rc(tid * 16 + i * 8192, R, C); const int Rb = Epi::PERM ? ((R & ~31) + perm32(R & 31)) : R;
;         voffA[i] = (unsigned)(R * g.ld + C) * 2u; voffB[i] = (unsigned)(Rb * g.ld + C) * 2u; }
;     const size_t kstep = (size_t)(BK * 2);
;     const size_t hstep = (size_t)HALF * g.ld * 2;
;     const size_t tstep = 2 * hstep;
;     const unsigned ldsw = (unsigned)wid * 1024u;
;     const int aoff = lds_byte(wr * 64 + fr, fq * 8), boff = lds_byte(wc * 32 + fr, fq * 8);
;     ...
;         PG8_STAGE(PG8_SB(0, 0), cB, voffB); PG8_STAGE(PG8_SB(0, 1), cB + hstep, voffB); PG8_STAGE(PG8_SA(0, 0), cA, voffA); PG8_STAGE(PG8_SA(0, 1), cA + hstep, voffA);
;         if (wr == 1) PG8_BAR;
;         PG8_WAIT_V(2); PG8_BAR;
;         PG8_STAGE(PG8_SB(1, 0), cB + kstep, voffB); PG8_STAGE(PG8_SA(1, 0), cA + kstep, voffA); PG8_STAGE(PG8_SB(1, 1), cB + hstep + kstep, voffB);
;         PG8_WAIT_V(6); PG8_BAR;
.LBB0_1836:
	s_add_u32 s8, s10, 0x62c0000
	s_addc_u32 s9, s11, 0
	s_add_u32 s10, s10, 0xbc20000
	s_addc_u32 s11, s11, 0
	s_lshl_b32 s3, s3, 5
	s_mov_b64 s[12:13], 0x80
	s_and_b32 s3, s3, 0x60
	s_add_i32 m0, s27, 0x18000
	v_lshl_add_u64 v[6:7], v[6:7], 0, s[12:13]
	s_lshl_b32 s4, s2, 13
	s_lshl_b32 s15, s3, 7
	s_waitcnt vmcnt(2)
	s_barrier
	global_load_lds_dwordx4 v[6:7], off
	v_lshl_add_u64 v[4:5], v[4:5], 0, s[12:13]
	s_add_i32 m0, s27, 0x1a000
	s_add_i32 s54, s27, 0x8000
	s_add_i32 s55, s27, 0xa000
	global_load_lds_dwordx4 v[4:5], off
	v_lshl_add_u64 v[0:1], v[0:1], 0, s[12:13]
	s_mov_b32 m0, s54
	s_add_u32 s16, s44, 0x20080
	global_load_lds_dwordx4 v[0:1], off
	v_lshl_add_u64 v[0:1], v[2:3], 0, s[12:13]
	s_mov_b32 m0, s55
	s_addc_u32 s17, s45, 0
	global_load_lds_dwordx4 v[0:1], off
	s_add_i32 m0, s27, 0x1c000
	v_lshl_add_u64 v[0:1], s[16:17], 0, v[130:131]
	global_load_lds_dwordx4 v[0:1], off
	v_lshl_add_u64 v[0:1], s[16:17], 0, v[134:135]
	s_add_i32 m0, s27, 0x1e000
	v_lshlrev_b32_e32 v2, 2, v180
	global_load_lds_dwordx4 v[0:1], off
	v_and_b32_e32 v0, 15, v180
	v_lshl_or_b32 v148, s2, 6, v0
	v_lshlrev_b32_e32 v1, 1, v11
	v_lshlrev_b32_e32 v3, 6, v180
	s_movk_i32 s2, 0x3c0
	v_lshl_or_b32 v0, v0, 6, v1
	v_and_b32_e32 v2, 32, v2
	v_and_or_b32 v1, v3, s2, v1
	v_bitop3_b32 v149, s15, v1, v2 bitop3:0xf6
	v_lshlrev_b32_e32 v1, 7, v180
	v_bitop3_b32 v0, v0, s4, v2 bitop3:0xde
	v_and_b32_e32 v1, 0x1c000, v1
	v_lshlrev_b32_e32 v2, 10, v10
	v_or3_b32 v1, v8, v1, v2
	v_add_u32_e32 v136, v1, v9
	v_lshlrev_b32_e32 v1, 3, v12
	s_waitcnt vmcnt(6)
	s_cmpk_lt_u32 s14, 0x100
	v_and_b32_e32 v1, 0x3c000, v1
	s_cselect_b64 s[14:15], -1, 0
	v_or3_b32 v1, v8, v1, v2
	s_add_i32 s57, 0, 0x10000
	s_add_i32 s58, 0, 0x14000
	s_ashr_i32 s56, s33, 31
	v_or_b32_e32 v150, s3, v11
	v_mov_b32_e32 v137, v131
	v_add_u32_e32 v138, v1, v9
	v_mov_b32_e32 v139, v131
	v_mov_b64_e32 v[140:141], 0x100
	v_mov_b64_e32 v[142:143], 0xff
	v_add_u32_e32 v151, s57, v149
	v_add_u32_e32 v152, s58, v149
	v_add_u32_e32 v153, 0, v0
	s_movk_i32 s59, 0x4080
	s_mov_b32 s4, s5
	s_barrier
	s_branch .LBB0_1839
